# k26: k24 + sample-path S5 item: LDS fill loads batched (six loads in flight instead of serialized triples), Bbar / d_skip / initial state / abar loads issued with them at the start of the item
# speedup vs baseline: 1.0183x; 1.0081x over previous
; __host__ __device__ __forceinline__ size_t ux_off(int m, int ch) { return ((size_t)((ch >> 4) * UXROWS + (m >> 4)) * UXR + (m & 15)) * 16 + (ch & 15); }
; __device__ __forceinline__ f32x2 cmul(f32x2 a, f32x2 b) { return (f32x2){a.x * b.x - a.y * b.y, a.x * b.y + a.y * b.x}; }
; __global__ void __launch_bounds__(NTHR, 2) hymba_fwd(Params P) {
;     ...
;         for (int i = tid; i < 1024; i += NTHR) { const int t = i >> 4, p = i & 15, s = b * 64 + t; US[i] = bf2f(UX[ux_off(PT + s, g * 16 + p)]);
;             CR[(i >> 6) * 65 + (i & 63)] = P.c_re[g * 1024 + i]; CI[(i >> 6) * 65 + (i & 63)] = P.c_im[g * 1024 + i]; }
;         __syncthreads();
;         { const int n = lane; f32x2 bb[16];
; #pragma unroll
;           for (int p = 0; p < 16; ++p) bb[p] = BBAR[(g * 64 + n) * 16 + p];
; #pragma unroll
;           for (int tt = 0; tt < 8; ++tt) { const int t = wave * 8 + tt; f32x2 bu = {0.f, 0.f};
; #pragma unroll
;               for (int p = 0; p < 16; ++p) { const float uu = US[t * 16 + p]; bu.x += bb[p].x * uu; bu.y += bb[p].y * uu; }
;               XS[t * 65 + n] = bu; } }
;         __syncthreads();
;         if (wave == 0) { const int n = lane; f32x2 xst = {P.st_re[(b * NG + g) * 64 + n], P.st_im[(b * NG + g) * 64 + n]}; const f32x2 ab = ABAR[g * 64 + n];
; #pragma unroll 8
;             for (int t = 0; t < 64; ++t) { const f32x2 bu = XS[t * 65 + n]; const f32x2 ax = cmul(ab, xst); xst = (f32x2){ax.x + bu.x, ax.y + bu.y}; XS[t * 65 + n] = xst; }
;             out[O_RS + (b * NG + g) * 64 + n] = xst.x; out[O_IS + (b * NG + g) * 64 + n] = xst.y; }
;         __syncthreads();
;         { const int t = tid >> 3, pp = tid & 7;
; #pragma unroll
;           for (int e = 0; e < 2; ++e) { const int p = pp + 8 * e; float y = P.d_skip[g * 16 + p] * US[t * 16 + p];
.LBB0_622:
	v_add_u32_e32 v62, 0x200, v7
	v_ashrrev_i32_e32 v60, 4, v7
	v_add_u32_e32 v61, s50, v60
	v_ashrrev_i32_e32 v61, 4, v61
	v_add_u32_e32 v61, s51, v61
	v_and_b32_e32 v32, 15, v60
	v_mad_i64_i32 v[64:65], s[52:53], v61, 24, v[32:33]
	v_lshlrev_b64 v[64:65], 5, v[64:65]
	v_lshl_add_u64 v[64:65], v[0:1], 0, v[64:65]
	global_load_ushort v70, v[64:65], off
	v_ashrrev_i32_e32 v60, 4, v62
	v_add_u32_e32 v61, s50, v60
	v_ashrrev_i32_e32 v61, 4, v61
	v_add_u32_e32 v61, s51, v61
	v_and_b32_e32 v32, 15, v60
	v_mad_i64_i32 v[66:67], s[52:53], v61, 24, v[32:33]
	v_lshlrev_b64 v[66:67], 5, v[66:67]
	v_lshl_add_u64 v[66:67], v[0:1], 0, v[66:67]
	global_load_ushort v71, v[66:67], off
	global_load_dword v72, v[2:3], off
	global_load_dword v73, v[2:3], off offset:2048
	global_load_dword v74, v[4:5], off
	global_load_dword v75, v[4:5], off offset:2048
	v_readlane_b32 s52, v255, 10
	v_readlane_b32 s53, v255, 11
	v_lshlrev_b32_e32 v78, 4, v34
	v_or_b32_e32 v78, s45, v78
	v_lshlrev_b32_e32 v78, 3, v78
	global_load_dwordx4 v[80:83], v78, s[52:53]
	global_load_dwordx4 v[84:87], v78, s[52:53] offset:16
	global_load_dwordx4 v[88:91], v78, s[52:53] offset:32
	global_load_dwordx4 v[92:95], v78, s[52:53] offset:48
	global_load_dwordx4 v[96:99], v78, s[52:53] offset:64
	global_load_dwordx4 v[100:103], v78, s[52:53] offset:80
	global_load_dwordx4 v[104:107], v78, s[52:53] offset:96
	global_load_dwordx4 v[108:111], v78, s[52:53] offset:112
	v_and_b32_e32 v77, 7, v35
	s_lshl_b32 s52, s35, 4
	v_or_b32_e32 v77, s52, v77
	v_lshlrev_b32_e32 v77, 2, v77
	global_load_dword v76, v77, s[82:83]
	s_lshl_b32 s52, s34, 6
	v_or_b32_e32 v79, s52, v34
	v_lshlrev_b32_e32 v79, 2, v79
	global_load_dword v112, v79, s[46:47]
	global_load_dword v113, v79, s[48:49]
	v_readlane_b32 s52, v255, 6
	v_readlane_b32 s53, v255, 7
	v_lshlrev_b32_e32 v79, 3, v34
	v_lshl_or_b32 v79, s35, 9, v79
	s_nop 1
	global_load_dwordx2 v[114:115], v79, s[52:53]
	s_movk_i32 s52, 0x41
	v_ashrrev_i32_e32 v60, 6, v7
	v_mad_u32_u24 v60, v60, s52, v34
	v_lshlrev_b32_e32 v60, 2, v60
	v_ashrrev_i32_e32 v61, 6, v62
	v_mad_u32_u24 v61, v61, s52, v34
	v_lshlrev_b32_e32 v61, 2, v61
	s_waitcnt vmcnt(17)
	v_lshlrev_b32_e32 v70, 16, v70
	ds_write_b32 v6, v70
	s_waitcnt vmcnt(16)
	v_lshlrev_b32_e32 v71, 16, v71
	ds_write_b32 v6, v71 offset:2048
	s_waitcnt vmcnt(15)
	ds_write_b32 v60, v72 offset:37376
	s_waitcnt vmcnt(14)
	ds_write_b32 v61, v73 offset:37376
	s_waitcnt vmcnt(13)
	ds_write_b32 v60, v74 offset:41536
	s_waitcnt vmcnt(12)
	ds_write_b32 v61, v75 offset:41536
	s_or_b64 exec, exec, s[12:13]
	v_mov_b32_e32 v0, s45
.LBB0_624:
	s_or_b64 exec, exec, s[10:11]
	v_readlane_b32 s10, v255, 10
	v_lshl_or_b32 v32, v34, 4, v0
	v_readlane_b32 s11, v255, 11
	s_waitcnt lgkmcnt(0)
	s_barrier
	v_lshl_add_u64 v[16:17], v[32:33], 3, s[10:11]
	s_waitcnt vmcnt(4)
	v_mov_b64_e32 v[12:13], v[80:81]
	v_mov_b64_e32 v[14:15], v[82:83]
	v_mov_b64_e32 v[8:9], v[84:85]
	v_mov_b64_e32 v[10:11], v[86:87]
	v_mov_b64_e32 v[4:5], v[88:89]
	v_mov_b64_e32 v[6:7], v[90:91]
	v_mov_b64_e32 v[0:1], v[92:93]
	v_mov_b64_e32 v[2:3], v[94:95]
	v_mov_b64_e32 v[28:29], v[96:97]
	v_mov_b64_e32 v[30:31], v[98:99]
	v_mov_b64_e32 v[24:25], v[100:101]
	v_mov_b64_e32 v[26:27], v[102:103]
	v_mov_b64_e32 v[20:21], v[104:105]
	v_mov_b64_e32 v[22:23], v[106:107]
	s_nop 0
	v_mov_b64_e32 v[16:17], v[108:109]
	v_mov_b64_e32 v[18:19], v[110:111]
	s_ashr_i32 s10, s44, 3
	s_and_b32 s11, s10, -8
	s_lshl_b32 s12, s11, 6
	s_add_i32 s12, s12, 0
	v_mov_b32_e32 v55, s12
	ds_read_b128 v[36:39], v55 offset:33280
	ds_read_b128 v[40:43], v55 offset:33296
	ds_read_b128 v[44:47], v55 offset:33312
	ds_read_b128 v[48:51], v55 offset:33328
	v_lshl_add_u32 v32, v34, 3, 0
	s_waitcnt lgkmcnt(3)
	v_mov_b32_e32 v52, v39
	s_waitcnt lgkmcnt(2)
	v_mov_b32_e32 v54, v43
	s_mulk_i32 s11, 0x208
	v_add_u32_e32 v57, s11, v32
	s_waitcnt lgkmcnt(1)
	v_mov_b32_e32 v56, v47
	s_waitcnt lgkmcnt(0)
	v_mov_b32_e32 v58, v51
	s_or_b32 s10, s10, 7
	s_lshl_b32 s11, s10, 6
	s_mulk_i32 s10, 0x208
	s_add_i32 s11, s11, 0
	s_cmp_lt_u32 s44, 64
	s_waitcnt vmcnt(7)
	v_pk_fma_f32 v[60:61], v[36:37], v[12:13], 0 op_sel_hi:[0,1,0]
	v_pk_fma_f32 v[36:37], v[36:37], v[14:15], v[60:61] op_sel:[1,0,0]
	s_waitcnt vmcnt(6)
	v_pk_fma_f32 v[36:37], v[38:39], v[8:9], v[36:37] op_sel_hi:[0,1,1]
	v_pk_fma_f32 v[36:37], v[52:53], v[10:11], v[36:37] op_sel_hi:[0,1,1]
	s_waitcnt vmcnt(5)
	v_pk_fma_f32 v[36:37], v[40:41], v[4:5], v[36:37] op_sel_hi:[0,1,1]
	v_pk_fma_f32 v[36:37], v[40:41], v[6:7], v[36:37] op_sel:[1,0,0]
	s_waitcnt vmcnt(4)
	v_pk_fma_f32 v[36:37], v[42:43], v[0:1], v[36:37] op_sel_hi:[0,1,1]
	v_pk_fma_f32 v[36:37], v[54:55], v[2:3], v[36:37] op_sel_hi:[0,1,1]
	s_waitcnt vmcnt(3)
	v_pk_fma_f32 v[36:37], v[44:45], v[28:29], v[36:37] op_sel_hi:[0,1,1]
	v_pk_fma_f32 v[36:37], v[44:45], v[30:31], v[36:37] op_sel:[1,0,0]
	s_waitcnt vmcnt(2)
	v_pk_fma_f32 v[36:37], v[46:47], v[24:25], v[36:37] op_sel_hi:[0,1,1]
	v_pk_fma_f32 v[36:37], v[56:57], v[26:27], v[36:37] op_sel_hi:[0,1,1]
	s_waitcnt vmcnt(1)
	v_pk_fma_f32 v[36:37], v[48:49], v[20:21], v[36:37] op_sel_hi:[0,1,1]
	v_pk_fma_f32 v[36:37], v[48:49], v[22:23], v[36:37] op_sel:[1,0,0]
	s_waitcnt vmcnt(0)
	v_pk_fma_f32 v[36:37], v[50:51], v[16:17], v[36:37] op_sel_hi:[0,1,1]
	v_pk_fma_f32 v[36:37], v[58:59], v[18:19], v[36:37] op_sel_hi:[0,1,1]
	ds_write_b64 v57, v[36:37]
	ds_read_b128 v[36:39], v55 offset:33344
	ds_read_b128 v[40:43], v55 offset:33360
	ds_read_b128 v[44:47], v55 offset:33376
	ds_read_b128 v[48:51], v55 offset:33392
	s_waitcnt lgkmcnt(2)
; __global__ void __launch_bounds__(NTHR, 2) hymba_fwd(Params P) {
;     ...
;           for (int tt = 0; tt < 8; ++tt) { const int t = wave * 8 + tt; f32x2 bu = {0.f, 0.f};
; #pragma unroll
;               for (int p = 0; p < 16; ++p) { const float uu = US[t * 16 + p]; bu.x += bb[p].x * uu; bu.y += bb[p].y * uu; }
;               XS[t * 65 + n] = bu; } }
	v_mov_b32_e32 v56, v43
	v_pk_fma_f32 v[52:53], v[36:37], v[12:13], 0 op_sel_hi:[0,1,0]
	v_pk_fma_f32 v[36:37], v[36:37], v[14:15], v[52:53] op_sel:[1,0,0]
	v_mov_b32_e32 v54, v39
	v_pk_fma_f32 v[36:37], v[38:39], v[8:9], v[36:37] op_sel_hi:[0,1,1]
	v_pk_fma_f32 v[36:37], v[54:55], v[10:11], v[36:37] op_sel_hi:[0,1,1]
	v_pk_fma_f32 v[36:37], v[40:41], v[4:5], v[36:37] op_sel_hi:[0,1,1]
	v_pk_fma_f32 v[36:37], v[40:41], v[6:7], v[36:37] op_sel:[1,0,0]
	s_waitcnt lgkmcnt(1)
	v_mov_b32_e32 v58, v47
	v_pk_fma_f32 v[36:37], v[42:43], v[0:1], v[36:37] op_sel_hi:[0,1,1]
	v_pk_fma_f32 v[36:37], v[56:57], v[2:3], v[36:37] op_sel_hi:[0,1,1]
	v_pk_fma_f32 v[36:37], v[44:45], v[28:29], v[36:37] op_sel_hi:[0,1,1]
	v_pk_fma_f32 v[36:37], v[44:45], v[30:31], v[36:37] op_sel:[1,0,0]
	s_waitcnt lgkmcnt(0)
	v_mov_b32_e32 v60, v51
	v_pk_fma_f32 v[36:37], v[46:47], v[24:25], v[36:37] op_sel_hi:[0,1,1]
	v_pk_fma_f32 v[36:37], v[58:59], v[26:27], v[36:37] op_sel_hi:[0,1,1]
	v_pk_fma_f32 v[36:37], v[48:49], v[20:21], v[36:37] op_sel_hi:[0,1,1]
	v_pk_fma_f32 v[36:37], v[48:49], v[22:23], v[36:37] op_sel:[1,0,0]
	s_nop 0
	v_pk_fma_f32 v[36:37], v[50:51], v[16:17], v[36:37] op_sel_hi:[0,1,1]
	v_pk_fma_f32 v[36:37], v[60:61], v[18:19], v[36:37] op_sel_hi:[0,1,1]
	ds_write_b64 v57, v[36:37] offset:520
	ds_read_b128 v[36:39], v55 offset:33408
	ds_read_b128 v[40:43], v55 offset:33424
	ds_read_b128 v[44:47], v55 offset:33440
	ds_read_b128 v[48:51], v55 offset:33456
	s_waitcnt lgkmcnt(2)
	v_mov_b32_e32 v56, v43
	v_pk_fma_f32 v[52:53], v[36:37], v[12:13], 0 op_sel_hi:[0,1,0]
	v_pk_fma_f32 v[36:37], v[36:37], v[14:15], v[52:53] op_sel:[1,0,0]
	v_mov_b32_e32 v54, v39
	v_pk_fma_f32 v[36:37], v[38:39], v[8:9], v[36:37] op_sel_hi:[0,1,1]
	v_pk_fma_f32 v[36:37], v[54:55], v[10:11], v[36:37] op_sel_hi:[0,1,1]
	v_pk_fma_f32 v[36:37], v[40:41], v[4:5], v[36:37] op_sel_hi:[0,1,1]
	v_pk_fma_f32 v[36:37], v[40:41], v[6:7], v[36:37] op_sel:[1,0,0]
	s_waitcnt lgkmcnt(1)
	v_mov_b32_e32 v58, v47
	v_pk_fma_f32 v[36:37], v[42:43], v[0:1], v[36:37] op_sel_hi:[0,1,1]
	v_pk_fma_f32 v[36:37], v[56:57], v[2:3], v[36:37] op_sel_hi:[0,1,1]
	v_pk_fma_f32 v[36:37], v[44:45], v[28:29], v[36:37] op_sel_hi:[0,1,1]
	v_pk_fma_f32 v[36:37], v[44:45], v[30:31], v[36:37] op_sel:[1,0,0]
	s_waitcnt lgkmcnt(0)
	v_mov_b32_e32 v60, v51
	v_pk_fma_f32 v[36:37], v[46:47], v[24:25], v[36:37] op_sel_hi:[0,1,1]
	v_pk_fma_f32 v[36:37], v[58:59], v[26:27], v[36:37] op_sel_hi:[0,1,1]
	v_pk_fma_f32 v[36:37], v[48:49], v[20:21], v[36:37] op_sel_hi:[0,1,1]
	v_pk_fma_f32 v[36:37], v[48:49], v[22:23], v[36:37] op_sel:[1,0,0]
	s_nop 0
	v_pk_fma_f32 v[36:37], v[50:51], v[16:17], v[36:37] op_sel_hi:[0,1,1]
	v_pk_fma_f32 v[36:37], v[60:61], v[18:19], v[36:37] op_sel_hi:[0,1,1]
	ds_write_b64 v57, v[36:37] offset:1040
	ds_read_b128 v[36:39], v55 offset:33472
	ds_read_b128 v[40:43], v55 offset:33488
	ds_read_b128 v[44:47], v55 offset:33504
	ds_read_b128 v[48:51], v55 offset:33520
	s_waitcnt lgkmcnt(2)
	v_mov_b32_e32 v56, v43
	v_pk_fma_f32 v[52:53], v[36:37], v[12:13], 0 op_sel_hi:[0,1,0]
	v_pk_fma_f32 v[36:37], v[36:37], v[14:15], v[52:53] op_sel:[1,0,0]
	v_mov_b32_e32 v54, v39
	v_pk_fma_f32 v[36:37], v[38:39], v[8:9], v[36:37] op_sel_hi:[0,1,1]
	v_pk_fma_f32 v[36:37], v[54:55], v[10:11], v[36:37] op_sel_hi:[0,1,1]
	v_pk_fma_f32 v[36:37], v[40:41], v[4:5], v[36:37] op_sel_hi:[0,1,1]
	v_pk_fma_f32 v[36:37], v[40:41], v[6:7], v[36:37] op_sel:[1,0,0]
	s_waitcnt lgkmcnt(1)
	v_mov_b32_e32 v58, v47
	v_pk_fma_f32 v[36:37], v[42:43], v[0:1], v[36:37] op_sel_hi:[0,1,1]
	v_pk_fma_f32 v[36:37], v[56:57], v[2:3], v[36:37] op_sel_hi:[0,1,1]
	v_pk_fma_f32 v[36:37], v[44:45], v[28:29], v[36:37] op_sel_hi:[0,1,1]
	v_pk_fma_f32 v[36:37], v[44:45], v[30:31], v[36:37] op_sel:[1,0,0]
	s_waitcnt lgkmcnt(0)
	v_mov_b32_e32 v60, v51
	v_pk_fma_f32 v[36:37], v[46:47], v[24:25], v[36:37] op_sel_hi:[0,1,1]
	v_pk_fma_f32 v[36:37], v[58:59], v[26:27], v[36:37] op_sel_hi:[0,1,1]
	v_pk_fma_f32 v[36:37], v[48:49], v[20:21], v[36:37] op_sel_hi:[0,1,1]
	v_pk_fma_f32 v[36:37], v[48:49], v[22:23], v[36:37] op_sel:[1,0,0]
	s_nop 0
	v_pk_fma_f32 v[36:37], v[50:51], v[16:17], v[36:37] op_sel_hi:[0,1,1]
	v_pk_fma_f32 v[36:37], v[60:61], v[18:19], v[36:37] op_sel_hi:[0,1,1]
	ds_write_b64 v57, v[36:37] offset:1560
	ds_read_b128 v[36:39], v55 offset:33536
	ds_read_b128 v[40:43], v55 offset:33552
	ds_read_b128 v[44:47], v55 offset:33568
	ds_read_b128 v[48:51], v55 offset:33584
	s_waitcnt lgkmcnt(2)
	v_mov_b32_e32 v56, v43
	v_pk_fma_f32 v[52:53], v[36:37], v[12:13], 0 op_sel_hi:[0,1,0]
	v_pk_fma_f32 v[36:37], v[36:37], v[14:15], v[52:53] op_sel:[1,0,0]
	v_mov_b32_e32 v54, v39
	v_pk_fma_f32 v[36:37], v[38:39], v[8:9], v[36:37] op_sel_hi:[0,1,1]
	v_pk_fma_f32 v[36:37], v[54:55], v[10:11], v[36:37] op_sel_hi:[0,1,1]
	v_pk_fma_f32 v[36:37], v[40:41], v[4:5], v[36:37] op_sel_hi:[0,1,1]
	v_pk_fma_f32 v[36:37], v[40:41], v[6:7], v[36:37] op_sel:[1,0,0]
	s_waitcnt lgkmcnt(1)
	v_mov_b32_e32 v58, v47
	v_pk_fma_f32 v[36:37], v[42:43], v[0:1], v[36:37] op_sel_hi:[0,1,1]
	v_pk_fma_f32 v[36:37], v[56:57], v[2:3], v[36:37] op_sel_hi:[0,1,1]
	v_pk_fma_f32 v[36:37], v[44:45], v[28:29], v[36:37] op_sel_hi:[0,1,1]
	v_pk_fma_f32 v[36:37], v[44:45], v[30:31], v[36:37] op_sel:[1,0,0]
	s_waitcnt lgkmcnt(0)
; __global__ void __launch_bounds__(NTHR, 2) hymba_fwd(Params P) {
;     ...
;           for (int tt = 0; tt < 8; ++tt) { const int t = wave * 8 + tt; f32x2 bu = {0.f, 0.f};
; #pragma unroll
;               for (int p = 0; p < 16; ++p) { const float uu = US[t * 16 + p]; bu.x += bb[p].x * uu; bu.y += bb[p].y * uu; }
;               XS[t * 65 + n] = bu; } }
;         __syncthreads();
;         if (wave == 0) { const int n = lane; f32x2 xst = {P.st_re[(b * NG + g) * 64 + n], P.st_im[(b * NG + g) * 64 + n]}; const f32x2 ab = ABAR[g * 64 + n];
	v_mov_b32_e32 v60, v51
	v_pk_fma_f32 v[36:37], v[46:47], v[24:25], v[36:37] op_sel_hi:[0,1,1]
	v_pk_fma_f32 v[36:37], v[58:59], v[26:27], v[36:37] op_sel_hi:[0,1,1]
	v_pk_fma_f32 v[36:37], v[48:49], v[20:21], v[36:37] op_sel_hi:[0,1,1]
	v_pk_fma_f32 v[36:37], v[48:49], v[22:23], v[36:37] op_sel:[1,0,0]
	v_add_u32_e32 v59, s10, v32
	v_pk_fma_f32 v[36:37], v[50:51], v[16:17], v[36:37] op_sel_hi:[0,1,1]
	v_pk_fma_f32 v[36:37], v[60:61], v[18:19], v[36:37] op_sel_hi:[0,1,1]
	ds_write_b64 v57, v[36:37] offset:2080
	ds_read_b128 v[36:39], v55 offset:33600
	ds_read_b128 v[40:43], v55 offset:33616
	ds_read_b128 v[44:47], v55 offset:33632
	ds_read_b128 v[48:51], v55 offset:33648
	s_waitcnt lgkmcnt(2)
	v_mov_b32_e32 v56, v43
	v_pk_fma_f32 v[52:53], v[36:37], v[12:13], 0 op_sel_hi:[0,1,0]
	v_pk_fma_f32 v[36:37], v[36:37], v[14:15], v[52:53] op_sel:[1,0,0]
	v_mov_b32_e32 v54, v39
	v_pk_fma_f32 v[36:37], v[38:39], v[8:9], v[36:37] op_sel_hi:[0,1,1]
	v_pk_fma_f32 v[36:37], v[54:55], v[10:11], v[36:37] op_sel_hi:[0,1,1]
	v_pk_fma_f32 v[36:37], v[40:41], v[4:5], v[36:37] op_sel_hi:[0,1,1]
	v_pk_fma_f32 v[36:37], v[40:41], v[6:7], v[36:37] op_sel:[1,0,0]
	s_waitcnt lgkmcnt(1)
	v_mov_b32_e32 v58, v47
	v_pk_fma_f32 v[36:37], v[42:43], v[0:1], v[36:37] op_sel_hi:[0,1,1]
	v_pk_fma_f32 v[36:37], v[56:57], v[2:3], v[36:37] op_sel_hi:[0,1,1]
	v_pk_fma_f32 v[36:37], v[44:45], v[28:29], v[36:37] op_sel_hi:[0,1,1]
	v_pk_fma_f32 v[36:37], v[44:45], v[30:31], v[36:37] op_sel:[1,0,0]
	s_waitcnt lgkmcnt(0)
	v_mov_b32_e32 v60, v51
	v_pk_fma_f32 v[36:37], v[46:47], v[24:25], v[36:37] op_sel_hi:[0,1,1]
	v_pk_fma_f32 v[36:37], v[58:59], v[26:27], v[36:37] op_sel_hi:[0,1,1]
	v_pk_fma_f32 v[36:37], v[48:49], v[20:21], v[36:37] op_sel_hi:[0,1,1]
	v_pk_fma_f32 v[36:37], v[48:49], v[22:23], v[36:37] op_sel:[1,0,0]
	s_nop 0
	v_pk_fma_f32 v[36:37], v[50:51], v[16:17], v[36:37] op_sel_hi:[0,1,1]
	v_pk_fma_f32 v[36:37], v[60:61], v[18:19], v[36:37] op_sel_hi:[0,1,1]
	ds_write_b64 v57, v[36:37] offset:2600
	ds_read_b128 v[36:39], v55 offset:33664
	ds_read_b128 v[40:43], v55 offset:33680
	ds_read_b128 v[44:47], v55 offset:33696
	ds_read_b128 v[48:51], v55 offset:33712
	v_mov_b32_e32 v61, s11
	s_waitcnt lgkmcnt(2)
	v_mov_b32_e32 v56, v43
	v_pk_fma_f32 v[52:53], v[36:37], v[12:13], 0 op_sel_hi:[0,1,0]
	v_pk_fma_f32 v[36:37], v[36:37], v[14:15], v[52:53] op_sel:[1,0,0]
	v_mov_b32_e32 v54, v39
	v_pk_fma_f32 v[36:37], v[38:39], v[8:9], v[36:37] op_sel_hi:[0,1,1]
	v_pk_fma_f32 v[36:37], v[54:55], v[10:11], v[36:37] op_sel_hi:[0,1,1]
	v_pk_fma_f32 v[36:37], v[40:41], v[4:5], v[36:37] op_sel_hi:[0,1,1]
	v_pk_fma_f32 v[36:37], v[40:41], v[6:7], v[36:37] op_sel:[1,0,0]
	s_waitcnt lgkmcnt(1)
	v_mov_b32_e32 v58, v47
	v_pk_fma_f32 v[36:37], v[42:43], v[0:1], v[36:37] op_sel_hi:[0,1,1]
	v_pk_fma_f32 v[36:37], v[56:57], v[2:3], v[36:37] op_sel_hi:[0,1,1]
	v_pk_fma_f32 v[36:37], v[44:45], v[28:29], v[36:37] op_sel_hi:[0,1,1]
	v_pk_fma_f32 v[36:37], v[44:45], v[30:31], v[36:37] op_sel:[1,0,0]
	s_waitcnt lgkmcnt(0)
	v_mov_b32_e32 v60, v51
	v_pk_fma_f32 v[36:37], v[46:47], v[24:25], v[36:37] op_sel_hi:[0,1,1]
	v_pk_fma_f32 v[36:37], v[58:59], v[26:27], v[36:37] op_sel_hi:[0,1,1]
	v_pk_fma_f32 v[36:37], v[48:49], v[20:21], v[36:37] op_sel_hi:[0,1,1]
	v_pk_fma_f32 v[36:37], v[48:49], v[22:23], v[36:37] op_sel:[1,0,0]
	s_nop 0
	v_pk_fma_f32 v[36:37], v[50:51], v[16:17], v[36:37] op_sel_hi:[0,1,1]
	v_pk_fma_f32 v[36:37], v[60:61], v[18:19], v[36:37] op_sel_hi:[0,1,1]
	ds_write_b64 v57, v[36:37] offset:3120
	ds_read_b128 v[36:39], v61 offset:33280
	ds_read_b128 v[40:43], v61 offset:33296
	ds_read_b128 v[44:47], v61 offset:33312
	ds_read_b128 v[48:51], v61 offset:33328
	s_waitcnt lgkmcnt(2)
	v_mov_b32_e32 v54, v43
	v_pk_fma_f32 v[12:13], v[36:37], v[12:13], 0 op_sel_hi:[0,1,0]
	v_pk_fma_f32 v[12:13], v[36:37], v[14:15], v[12:13] op_sel:[1,0,0]
	v_mov_b32_e32 v52, v39
	v_pk_fma_f32 v[8:9], v[38:39], v[8:9], v[12:13] op_sel_hi:[0,1,1]
	v_pk_fma_f32 v[8:9], v[52:53], v[10:11], v[8:9] op_sel_hi:[0,1,1]
	v_pk_fma_f32 v[4:5], v[40:41], v[4:5], v[8:9] op_sel_hi:[0,1,1]
	v_pk_fma_f32 v[4:5], v[40:41], v[6:7], v[4:5] op_sel:[1,0,0]
	s_waitcnt lgkmcnt(1)
	v_mov_b32_e32 v56, v47
	v_pk_fma_f32 v[0:1], v[42:43], v[0:1], v[4:5] op_sel_hi:[0,1,1]
	v_pk_fma_f32 v[0:1], v[54:55], v[2:3], v[0:1] op_sel_hi:[0,1,1]
	v_pk_fma_f32 v[0:1], v[44:45], v[28:29], v[0:1] op_sel_hi:[0,1,1]
	v_pk_fma_f32 v[0:1], v[44:45], v[30:31], v[0:1] op_sel:[1,0,0]
	s_waitcnt lgkmcnt(0)
	v_mov_b32_e32 v58, v51
	v_pk_fma_f32 v[0:1], v[46:47], v[24:25], v[0:1] op_sel_hi:[0,1,1]
	v_pk_fma_f32 v[0:1], v[56:57], v[26:27], v[0:1] op_sel_hi:[0,1,1]
	v_pk_fma_f32 v[0:1], v[48:49], v[20:21], v[0:1] op_sel_hi:[0,1,1]
	v_pk_fma_f32 v[0:1], v[48:49], v[22:23], v[0:1] op_sel:[1,0,0]
	s_nop 0
	v_pk_fma_f32 v[0:1], v[50:51], v[16:17], v[0:1] op_sel_hi:[0,1,1]
	v_pk_fma_f32 v[0:1], v[58:59], v[18:19], v[0:1] op_sel_hi:[0,1,1]
	ds_write_b64 v59, v[0:1]
	s_waitcnt lgkmcnt(0)
	s_barrier
	s_cbranch_scc0 .LBB0_628
	s_lshl_b32 s10, s34, 6
	v_or_b32_e32 v0, s10, v34
	v_ashrrev_i32_e32 v1, 31, v0
	v_lshlrev_b64 v[0:1], 2, v[0:1]
	v_lshl_add_u64 v[2:3], s[46:47], 0, v[0:1]
	v_lshl_add_u64 v[0:1], s[48:49], 0, v[0:1]
	s_waitcnt vmcnt(0)
	v_mov_b32_e32 v2, v112
	v_readlane_b32 s12, v255, 6
	v_mov_b32_e32 v3, v113
	v_lshlrev_b32_e32 v0, 3, v34
	v_lshl_or_b32 v0, s35, 9, v0
	v_readlane_b32 s13, v255, 7
	s_mov_b32 s11, 0
	s_nop 3
	v_mov_b64_e32 v[0:1], v[114:115]

; __global__ void __launch_bounds__(NTHR, 2) hymba_fwd(Params P) {
;     ...
;         { const int t = tid >> 3, pp = tid & 7;
; #pragma unroll
;           for (int e = 0; e < 2; ++e) { const int p = pp + 8 * e; float y = P.d_skip[g * 16 + p] * US[t * 16 + p];
.LBB0_628:
	v_and_b32_e32 v0, 7, v35
	s_lshl_b32 s10, s35, 4
	v_or_b32_e32 v1, s10, v0
	v_lshlrev_b32_e32 v1, 2, v1
	s_waitcnt lgkmcnt(0)
	s_barrier
	s_waitcnt vmcnt(0)
	v_mov_b32_e32 v3, v76
	v_ashrrev_i32_e32 v1, 3, v35
	v_lshlrev_b32_e32 v2, 6, v1
	v_lshlrev_b32_e32 v4, 2, v0
	v_add3_u32 v4, 0, v2, v4
	ds_read_b32 v6, v4 offset:33280
	v_mul_lo_u32 v2, v1, s20
	v_mul_u32_u24_e32 v5, 0x41, v0
	v_add_u32_e32 v2, 0, v2
	s_mov_b32 s11, 0
	v_lshl_add_u32 v5, v5, 2, s21
	s_waitcnt vmcnt(0) lgkmcnt(0)
	v_mul_f32_e32 v3, v3, v6
	v_mov_b32_e32 v6, v2
